# DeltaNet scan spread over all 256 workgroups: each (batch, head, direction) unit cut into four 32-column quarters (one state wave per workgroup, placed beside the light V/T helper), 4x fewer atomics p
# speedup vs baseline: 1.0459x; 1.0156x over previous
; __device__ __forceinline__ int opaque_tid() { int t = threadIdx.x; asm volatile("" : "+v"(t)); return t; }
; template <int VAR> __device__ __forceinline__ void dn_scan3(LAS unsigned char* lds, const bf16_t* P, const float* AB, const bf16_t* TP, bf16_t* OB) {
;     const int tid0 = opaque_tid(), wv = __builtin_amdgcn_readfirstlane(tid0 >> 6), role = wv >> 2, w = wv & 3;
;     for (int unit = blockIdx.x; unit < 64; unit += gridDim.x) {
;         const int b = unit >> 5, vh = (unit >> 1) & 15, dir = unit & 1, kh = vh >> 1;
;         __syncthreads();
;         if (role == 1) {
.LBB0_369:
	s_and_b64 vcc, exec, s[40:41]
	s_cbranch_vccz .LBB0_463
	v_readlane_b32 s4, v254, 62
	s_cmp_gt_i32 s4, 1
	s_mov_b64 s[4:5], -1
	v_readlane_b32 s16, v254, 57
	s_cbranch_scc0 .LBB0_466
	v_readlane_b32 s0, v254, 62
	s_cmp_gt_i32 s0, 2
	s_mov_b64 s[0:1], -1
	s_cbranch_scc0 .LBB0_465
	v_readlane_b32 s0, v251, 39
	s_waitcnt vmcnt(0)
	v_mov_b32_e32 v0, v188
	v_readlane_b32 s1, v251, 40
	v_readlane_b32 s4, v251, 37
	v_readlane_b32 s8, v254, 33
	s_andn2_b64 vcc, exec, s[0:1]
	v_readfirstlane_b32 s0, v0
	s_movk_i32 s67, 0x90
	v_readlane_b32 s68, v253, 36
	v_readlane_b32 s69, v253, 37
	v_readlane_b32 s74, v253, 38
	v_readlane_b32 s75, v253, 39
	v_readlane_b32 s5, v251, 38
	v_readlane_b32 s9, v254, 34
	s_cmpk_eq_i32 s78, 0x100
	s_cselect_b32 s64, 1, 0
	s_cbranch_scc0 .Ldn_nosplit
	s_mov_b64 vcc, 0
.Ldn_nosplit:
	s_cbranch_vccnz .LBB0_464
	s_bfe_u32 s40, s0, 0x20006
	s_and_b32 s0, s0, 0xffffff00
	s_cmpk_lg_i32 s0, 0x100
	s_cselect_b64 s[0:1], -1, 0
	s_lshl_b32 s18, s40, 6
	s_cmp_lg_u32 s40, 3
	s_cselect_b64 s[10:11], -1, 0
	s_cmp_eq_u32 s40, 0
	s_cselect_b32 s19, 0, 32
	s_cmp_eq_u32 s40, 2
	s_cselect_b32 s52, 32, 0
	s_lshl_b32 s40, s40, 8
	s_add_i32 s53, s40, 0
	v_readlane_b32 s40, v253, 20
	s_add_i32 s53, s53, 0x22c00
	s_mov_b32 s54, s40
	s_cmp_eq_u32 s64, 0
	s_cbranch_scc1 .Ldn_unit_done
	s_and_b32 s54, s40, 7
	s_lshr_b32 s65, s40, 5
	s_lshl_b32 s65, s65, 3
	s_add_i32 s54, s54, s65
	s_bfe_u32 s65, s40, 0x20003
.Ldn_unit_done:
	v_readlane_b32 s41, v253, 21
	s_branch .LBB0_375

; __device__ __forceinline__ int opaque_tid() { int t = threadIdx.x; asm volatile("" : "+v"(t)); return t; }
; #define LAS __attribute__((address_space(3)))
; #define BAR_LDS() do { asm volatile("s_waitcnt lgkmcnt(0)" ::: "memory"); __builtin_amdgcn_s_barrier(); asm volatile("" ::: "memory"); } while (0)
; #define MFMA32(a, b, c) __builtin_amdgcn_mfma_f32_32x32x16_bf16((a), (b), (c), 0, 0, 0)
; template <int VAR> __device__ __forceinline__ void dn_scan3(LAS unsigned char* lds, const bf16_t* P, const float* AB, const bf16_t* TP, bf16_t* OB) {
;     ...
;             f32x16 S[4];
; #pragma unroll
;             for (int kt = 0; kt < 4; ++kt)
; #pragma unroll
;                 for (int x = 0; x < 16; ++x) S[kt][x] = 0.f;
;             BAR_LDS();
;             for (int step = 0; step < 260; ++step) {
;                 const int lane = opaque_tid() & 63, r = lane & 31, h = lane >> 5;
;                 LAS unsigned char* base = lds + (step & 1) * DN_DIR;
;                 LAS bf16_t* Kb = (LAS bf16_t*)(base + DN_KB); LAS bf16_t* Qb = (LAS bf16_t*)(base + DN_QB); LAS bf16_t* Vb = (LAS bf16_t*)(base + DN_VB);
;                 LAS bf16_t* Tb = (LAS bf16_t*)(base + DN_TB); LAS bf16_t* Ab = (LAS bf16_t*)(base + DN_AB);
;                 LAS float* sc_beta = (LAS float*)(base + DN_SC); LAS float* sc_eg = sc_beta + 128; LAS float* sc_tail = sc_beta + 192; LAS float* sc_dl = sc_beta + 256;
;                 int rb; bool f_; dn_step_rb(step, dir, b, rb, f_);
;                 if (VAR != 2) {
;                 f32x16 KS[2], QS[2];
; #pragma unroll
;                 for (int mt = 0; mt < 2; ++mt)
; #pragma unroll
;                     for (int x = 0; x < 16; ++x) { KS[mt][x] = 0.f; QS[mt][x] = 0.f; }
; #pragma unroll
;                 for (int ks = 0; ks < 8; ++ks) {
;                     const bf16x8 sp = pack_step(S[ks >> 1], ks & 1);
; #pragma unroll
;                     for (int mt = 0; mt < 2; ++mt) { KS[mt] = MFMA32(frag_perm(Kb, 136, 32 * mt + r, ks, h), sp, KS[mt]); QS[mt] = MFMA32(frag_perm(Qb, 136, 32 * mt + r, ks, h), sp, QS[mt]); }
.LBB0_375:
	s_mov_b64 s[40:41], -1
	s_and_b64 vcc, exec, s[0:1]
	s_waitcnt lgkmcnt(0)
	s_barrier
	s_cbranch_vccz .LBB0_379
	s_waitcnt lgkmcnt(0)
	s_barrier
	s_cmp_eq_u32 s64, 0
	s_cbranch_scc1 .Ldn_full
	s_cmp_eq_u32 s18, 0xc0
	s_cbranch_scc1 .Ldn_lead
	s_movk_i32 s40, 0x104
.Ldn_idle:
	s_barrier
	s_add_i32 s40, s40, -1
	s_cmp_lg_u32 s40, 0
	s_cbranch_scc1 .Ldn_idle
	s_branch .Ldn_state_done
.Ldn_lead:
	s_lshl_b32 s18, s65, 6
.Ldn_full:
	v_mov_b32_e32 v2, 0
	s_mov_b32 s40, 0
	v_mov_b32_e32 v3, v2
	v_mov_b32_e32 v4, v2
	v_mov_b32_e32 v5, v2
	v_mov_b32_e32 v6, v2
	v_mov_b32_e32 v7, v2
	v_mov_b32_e32 v8, v2
	v_mov_b32_e32 v9, v2
	v_mov_b32_e32 v10, v2
	v_mov_b32_e32 v11, v2
	v_mov_b32_e32 v12, v2
	v_mov_b32_e32 v13, v2
	v_mov_b32_e32 v14, v2
	v_mov_b32_e32 v15, v2
	v_mov_b32_e32 v16, v2
	v_mov_b32_e32 v17, v2
	v_mov_b32_e32 v18, v2
	v_mov_b32_e32 v19, v2
	v_mov_b32_e32 v20, v2
	v_mov_b32_e32 v21, v2
	v_mov_b32_e32 v22, v2
	v_mov_b32_e32 v23, v2
	v_mov_b32_e32 v24, v2
	v_mov_b32_e32 v25, v2
	v_mov_b32_e32 v26, v2
	v_mov_b32_e32 v27, v2
	v_mov_b32_e32 v28, v2
	v_mov_b32_e32 v29, v2
	v_mov_b32_e32 v30, v2
	v_mov_b32_e32 v31, v2
	v_mov_b32_e32 v32, v2
	v_mov_b32_e32 v33, v2
	v_mov_b32_e32 v34, v2
	v_mov_b32_e32 v35, v2
	v_mov_b32_e32 v36, v2
	v_mov_b32_e32 v37, v2
	v_mov_b32_e32 v38, v2
	v_mov_b32_e32 v39, v2
	v_mov_b32_e32 v40, v2
	v_mov_b32_e32 v41, v2
	v_mov_b32_e32 v42, v2
	v_mov_b32_e32 v43, v2
	v_mov_b32_e32 v44, v2
	v_mov_b32_e32 v45, v2
	v_mov_b32_e32 v46, v2
	v_mov_b32_e32 v47, v2
	v_mov_b32_e32 v48, v2
	v_mov_b32_e32 v49, v2
	v_mov_b32_e32 v50, v2
	v_mov_b32_e32 v51, v2
	v_mov_b32_e32 v52, v2
	v_mov_b32_e32 v53, v2
	v_mov_b32_e32 v54, v2
	v_mov_b32_e32 v55, v2
	v_mov_b32_e32 v56, v2
	v_mov_b32_e32 v57, v2
	v_mov_b32_e32 v58, v2
	v_mov_b32_e32 v59, v2
	v_mov_b32_e32 v60, v2
	v_mov_b32_e32 v61, v2
	v_mov_b32_e32 v62, v2
	v_mov_b32_e32 v63, v2
	v_mov_b32_e32 v64, v2
	v_mov_b32_e32 v65, v2
	v_and_b32_e32 v212, 31, v188
	v_bfe_u32 v213, v188, 5, 1
	v_mul_u32_u24_e32 v214, 0x110, v212
	v_lshl_add_u32 v207, v213, 4, v214
	v_mul_u32_u24_e32 v214, 0x90, v212
	v_lshl_add_u32 v210, v213, 4, v214
	v_lshlrev_b32_e32 v214, 1, v212
	v_lshl_add_u32 v214, v213, 10, v214
	v_add_u32_e32 v208, s18, v214
	v_lshlrev_b32_e32 v214, 4, v213
	v_add_u32_e32 v209, 0x11000, v214
	v_bfe_u32 v214, v188, 2, 2
	v_and_b32_e32 v215, 3, v188
	v_lshlrev_b32_e32 v215, 3, v215
	v_bfe_u32 v216, v188, 4, 1
	v_lshl_add_u32 v215, v216, 5, v215
	v_lshlrev_b32_e32 v216, 3, v214
	v_lshl_add_u32 v216, v213, 2, v216
	v_and_b32_e32 v217, 3, v214
	v_add_u32_e32 v217, v217, v216
	v_mul_u32_u24_e32 v217, 0x110, v217
	v_add_u32_e32 v211, v217, v215
	v_add_u32_e32 v217, 1, v214
	v_and_b32_e32 v217, 3, v217
	v_add_u32_e32 v217, v217, v216
	v_mul_u32_u24_e32 v217, 0x110, v217
	v_add_u32_e32 v201, v217, v215
	v_add_u32_e32 v217, 2, v214
	v_and_b32_e32 v217, 3, v217
	v_add_u32_e32 v217, v217, v216
	v_mul_u32_u24_e32 v217, 0x110, v217
	v_add_u32_e32 v180, v217, v215
	v_add_u32_e32 v217, 3, v214
	v_and_b32_e32 v217, 3, v217
	v_add_u32_e32 v217, v217, v216
	v_mul_u32_u24_e32 v217, 0x110, v217
	v_add_u32_e32 v217, v217, v215
	v_lshl_or_b32 v180, v217, 16, v180
	s_and_b32 s57, s54, 1
	s_lshr_b32 s45, s54, 5
	s_lshl_b32 s55, s45, 2
	s_addk_i32 s55, 0x200
	s_lshl_b32 s56, s45, 8
	s_bfe_u32 s48, s54, 0x40001
	s_lshl_b32 s48, s48, 8
	s_add_i32 s48, s48, s18
	s_add_u32 s58, s8, s48
	s_addc_u32 s59, s9, 0
	s_mul_i32 s49, s57, 63
	s_mov_b32 s60, 0
	s_lshl_b32 s61, s57, 15
	s_sub_i32 s61, 0x4000, s61
	s_lshl_b32 s62, s61, 1
	v_and_b32_e32 v212, 63, v188
	v_lshrrev_b32_e32 v213, 4, v212
	v_and_b32_e32 v214, 15, v212
	v_lshlrev_b32_e32 v214, 2, v214
	v_lshl_add_u32 v0, v213, 8, v214
	v_add_u32_e32 v0, s18, v0
	v_xor_b32_e32 v215, s49, v213
	v_lshl_add_u32 v194, v215, 12, v214
.LBB0_377:
	s_bitcmp1_b32 s40, 0
	s_cselect_b32 s41, 0x11600, 0
	v_add_u32_e32 v212, s41, v207
	v_add_u32_e32 v214, s41, v209
	v_add_u32_e32 v213, s41, v208
	v_add_u32_e32 v215, s41, v210
	s_add_i32 s42, s41, 0x11400
	v_mov_b32_e32 v217, s42
	v_add_u32_e32 v179, s41, v0
	s_add_i32 s44, s40, -4
	s_cmp_lt_u32 s40, 4
	s_cselect_b32 s44, s40, s44
	s_cselect_b32 s45, 3, 0xff
	s_cselect_b32 s48, s55, s56
	s_sub_i32 s45, s45, s44
	s_cmp_eq_u32 s57, 0
	s_cselect_b32 s44, s44, s45
	s_add_i32 s44, s44, s48
	s_lshl_b32 s44, s44, 18
	s_add_u32 s42, s58, s44
	s_addc_u32 s43, s59, 0
	ds_read_b128 v[138:141], v212 offset:0
	ds_read_b128 v[142:145], v212 offset:32
	ds_read_b128 v[146:149], v212 offset:64
	ds_read_b128 v[150:153], v212 offset:96
	ds_read_b128 v[154:157], v212 offset:128
	ds_read_b128 v[158:161], v212 offset:160
	v_cvt_pk_bf16_f32 v218, v50, v51
	v_cvt_pk_bf16_f32 v220, v54, v55
	v_cvt_pk_bf16_f32 v219, v52, v53
	v_cvt_pk_bf16_f32 v221, v56, v57
	v_cvt_pk_bf16_f32 v222, v58, v59
	v_cvt_pk_bf16_f32 v224, v62, v63
	v_cvt_pk_bf16_f32 v223, v60, v61
	v_cvt_pk_bf16_f32 v225, v64, v65
	v_permlane32_swap_b32_e32 v218, v220
	v_permlane32_swap_b32_e32 v219, v221
	v_permlane32_swap_b32_e32 v222, v224
	v_permlane32_swap_b32_e32 v223, v225
	ds_read_b128 v[162:165], v212 offset:192
	ds_read_b128 v[166:169], v212 offset:224
	s_waitcnt lgkmcnt(7)
	v_mfma_f32_32x32x16_bf16 v[66:81], v[138:141], v[218:221], 0
	v_cvt_pk_bf16_f32 v226, v34, v35
	v_cvt_pk_bf16_f32 v228, v38, v39
	v_cvt_pk_bf16_f32 v227, v36, v37
	v_cvt_pk_bf16_f32 v229, v40, v41
	v_permlane32_swap_b32_e32 v226, v228
	ds_read_b128 v[138:141], v212 offset:8704
	v_permlane32_swap_b32_e32 v227, v229
	ds_read_b128 v[170:173], v212 offset:8736
	s_waitcnt lgkmcnt(8)
; #define LAS __attribute__((address_space(3)))
; #define MFMA32(a, b, c) __builtin_amdgcn_mfma_f32_32x32x16_bf16((a), (b), (c), 0, 0, 0)
; template <int VAR> __device__ __forceinline__ void dn_scan3(LAS unsigned char* lds, const bf16_t* P, const float* AB, const bf16_t* TP, bf16_t* OB) {
;     ...
;                 for (int ks = 0; ks < 8; ++ks) {
;                     const bf16x8 sp = pack_step(S[ks >> 1], ks & 1);
; #pragma unroll
;                     for (int mt = 0; mt < 2; ++mt) { KS[mt] = MFMA32(frag_perm(Kb, 136, 32 * mt + r, ks, h), sp, KS[mt]); QS[mt] = MFMA32(frag_perm(Qb, 136, 32 * mt + r, ks, h), sp, QS[mt]); }
;                 }
;                 __builtin_amdgcn_iglp_opt(0);
; #pragma unroll
;                 for (int mt = 0; mt < 2; ++mt)
; #pragma unroll
;                     for (int g4 = 0; g4 < 4; ++g4) { const int i0 = 32 * mt + 8 * g4 + 4 * h;
;                         const f32x4 bv = *(const LAS f32x4*)(sc_beta + i0), ev = *(const LAS f32x4*)(sc_eg + i0);
; #pragma unroll
;                         for (int e = 0; e < 4; ++e) { const int x = 4 * g4 + e; KS[mt][x] = bv[e] * (bf2f(Vb[(i0 + e) * 128 + 32 * w + r]) - ev[e] * KS[mt][x]); } }
;                 bf16x8 Xp[4];
; #pragma unroll
;                 for (int ks = 0; ks < 4; ++ks) Xp[ks] = pack_step(KS[ks >> 1], ks & 1);
	v_mfma_f32_32x32x16_bf16 v[66:81], v[142:145], v[222:225], v[66:81]
	v_cvt_pk_bf16_f32 v230, v42, v43
	v_cvt_pk_bf16_f32 v232, v46, v47
	v_cvt_pk_bf16_f32 v231, v44, v45
	v_cvt_pk_bf16_f32 v233, v48, v49
	v_permlane32_swap_b32_e32 v230, v232
	ds_read_b128 v[142:145], v212 offset:8768
	v_permlane32_swap_b32_e32 v231, v233
	s_waitcnt lgkmcnt(8)
	v_mfma_f32_32x32x16_bf16 v[66:81], v[146:149], v[226:229], v[66:81]
	v_cvt_pk_bf16_f32 v234, v18, v19
	v_cvt_pk_bf16_f32 v236, v22, v23
	v_cvt_pk_bf16_f32 v235, v20, v21
	v_cvt_pk_bf16_f32 v237, v24, v25
	v_permlane32_swap_b32_e32 v234, v236
	ds_read_b128 v[146:149], v212 offset:8800
	v_permlane32_swap_b32_e32 v235, v237
	s_waitcnt lgkmcnt(8)
	v_mfma_f32_32x32x16_bf16 v[66:81], v[150:153], v[230:233], v[66:81]
	v_cvt_pk_bf16_f32 v238, v26, v27
	v_cvt_pk_bf16_f32 v240, v30, v31
	v_cvt_pk_bf16_f32 v239, v28, v29
	v_cvt_pk_bf16_f32 v241, v32, v33
	v_permlane32_swap_b32_e32 v238, v240
	ds_read_b128 v[150:153], v212 offset:8832
	v_permlane32_swap_b32_e32 v239, v241
	s_waitcnt lgkmcnt(8)
	v_mfma_f32_32x32x16_bf16 v[66:81], v[154:157], v[234:237], v[66:81]
	v_cvt_pk_bf16_f32 v242, v2, v3
	v_cvt_pk_bf16_f32 v244, v6, v7
	v_cvt_pk_bf16_f32 v243, v4, v5
	v_cvt_pk_bf16_f32 v245, v8, v9
	v_permlane32_swap_b32_e32 v242, v244
	ds_read_b128 v[154:157], v212 offset:8864
	v_permlane32_swap_b32_e32 v243, v245
	s_waitcnt lgkmcnt(8)
	v_mfma_f32_32x32x16_bf16 v[66:81], v[158:161], v[238:241], v[66:81]
	v_cvt_pk_bf16_f32 v246, v10, v11
	v_cvt_pk_bf16_f32 v248, v14, v15
	v_cvt_pk_bf16_f32 v247, v12, v13
	v_cvt_pk_bf16_f32 v249, v16, v17
	v_permlane32_swap_b32_e32 v246, v248
	ds_read_b128 v[158:161], v212 offset:8896
	v_permlane32_swap_b32_e32 v247, v249
	ds_read_u16 v114, v213 offset:34816
	ds_read_u16 v115, v213 offset:35072
	ds_read_u16 v116, v213 offset:35328
	ds_read_u16 v117, v213 offset:35584
	ds_read_b128 v[118:121], v214 offset:0
	ds_read_b128 v[122:125], v214 offset:512
	s_waitcnt lgkmcnt(14)
	v_mfma_f32_32x32x16_bf16 v[66:81], v[162:165], v[242:245], v[66:81]
	ds_read_u16 v126, v213 offset:36864
	ds_read_u16 v127, v213 offset:37120
	ds_read_u16 v128, v213 offset:37376
	ds_read_u16 v129, v213 offset:37632
	ds_read_b128 v[130:133], v214 offset:32
	ds_read_b128 v[134:137], v214 offset:544
	ds_read_b128 v[162:165], v212 offset:8928
	v_mfma_f32_32x32x16_bf16 v[66:81], v[166:169], v[246:249], v[66:81]
	ds_read_b128 v[166:169], v212 offset:17408
	v_mfma_f32_32x32x16_bf16 v[82:97], v[138:141], v[218:221], 0
	ds_read_b128 v[138:141], v212 offset:17440
	v_mfma_f32_32x32x16_bf16 v[82:97], v[170:173], v[222:225], v[82:97]
	ds_read_b128 v[170:173], v212 offset:17472
	v_mfma_f32_32x32x16_bf16 v[82:97], v[142:145], v[226:229], v[82:97]
	v_lshlrev_b32_e32 v114, 16, v114
	s_waitcnt lgkmcnt(14)
	v_lshlrev_b32_e32 v115, 16, v115
	s_waitcnt lgkmcnt(13)
	v_lshlrev_b32_e32 v116, 16, v116
	s_waitcnt lgkmcnt(12)
	v_lshlrev_b32_e32 v117, 16, v117
	s_waitcnt lgkmcnt(10)
	v_fma_f32 v114, -v66, v122, v114
	v_fma_f32 v115, -v67, v123, v115
	v_fma_f32 v116, -v68, v124, v116
	v_fma_f32 v117, -v69, v125, v117
	v_mul_f32_e32 v66, v118, v114
	v_mul_f32_e32 v67, v119, v115
	v_mul_f32_e32 v68, v120, v116
	v_mul_f32_e32 v69, v121, v117
	ds_read_u16 v114, v213 offset:38912
	ds_read_u16 v115, v213 offset:39168
	ds_read_u16 v116, v213 offset:39424
	ds_read_u16 v117, v213 offset:39680
	ds_read_b128 v[118:121], v214 offset:64
	ds_read_b128 v[122:125], v214 offset:576
	ds_read_b128 v[142:145], v212 offset:17504
	v_mfma_f32_32x32x16_bf16 v[82:97], v[146:149], v[230:233], v[82:97]
	v_lshlrev_b32_e32 v126, 16, v126
	v_lshlrev_b32_e32 v127, 16, v127
	s_waitcnt lgkmcnt(14)
	v_lshlrev_b32_e32 v128, 16, v128
	s_waitcnt lgkmcnt(13)
	v_lshlrev_b32_e32 v129, 16, v129
	s_waitcnt lgkmcnt(11)
	v_fma_f32 v126, -v70, v134, v126
	v_fma_f32 v127, -v71, v135, v127
	v_fma_f32 v128, -v72, v136, v128
	v_fma_f32 v129, -v73, v137, v129
	v_mul_f32_e32 v70, v130, v126
	v_mul_f32_e32 v71, v131, v127
	v_mul_f32_e32 v72, v132, v128
	v_mul_f32_e32 v73, v133, v129
	ds_read_u16 v126, v213 offset:40960
	ds_read_u16 v127, v213 offset:41216
	ds_read_u16 v128, v213 offset:41472
	ds_read_u16 v129, v213 offset:41728
	ds_read_b128 v[130:133], v214 offset:96
	ds_read_b128 v[134:137], v214 offset:608
	ds_read_b128 v[146:149], v212 offset:17536
	v_mfma_f32_32x32x16_bf16 v[82:97], v[150:153], v[234:237], v[82:97]
	v_cvt_pk_bf16_f32 v150, v66, v67
	v_cvt_pk_bf16_f32 v152, v70, v71
	v_cvt_pk_bf16_f32 v151, v68, v69
	v_cvt_pk_bf16_f32 v153, v72, v73
	v_permlane32_swap_b32_e32 v150, v152
	s_nop 0
	v_permlane32_swap_b32_e32 v151, v153
	s_waitcnt lgkmcnt(13)
	v_lshlrev_b32_e32 v114, 16, v114
	s_waitcnt lgkmcnt(12)
	v_lshlrev_b32_e32 v115, 16, v115
	s_waitcnt lgkmcnt(11)
	v_lshlrev_b32_e32 v116, 16, v116
	s_waitcnt lgkmcnt(10)
	v_lshlrev_b32_e32 v117, 16, v117
	s_waitcnt lgkmcnt(8)
	v_fma_f32 v114, -v74, v122, v114
	v_fma_f32 v115, -v75, v123, v115
	v_fma_f32 v116, -v76, v124, v116
	v_fma_f32 v117, -v77, v125, v117
	v_mul_f32_e32 v74, v118, v114
	v_mul_f32_e32 v75, v119, v115
	v_mul_f32_e32 v76, v120, v116
	v_mul_f32_e32 v77, v121, v117
	v_mfma_f32_32x32x16_bf16 v[82:97], v[154:157], v[238:241], v[82:97]
	s_waitcnt lgkmcnt(6)
	v_lshlrev_b32_e32 v126, 16, v126
	s_waitcnt lgkmcnt(5)
	v_lshlrev_b32_e32 v127, 16, v127
	s_waitcnt lgkmcnt(4)
	v_lshlrev_b32_e32 v128, 16, v128
	s_waitcnt lgkmcnt(3)
	v_lshlrev_b32_e32 v129, 16, v129
	s_waitcnt lgkmcnt(1)
; template <int VAR> __device__ __forceinline__ void dn_scan3(LAS unsigned char* lds, const bf16_t* P, const float* AB, const bf16_t* TP, bf16_t* OB) {
;     ...
;                 for (int mt = 0; mt < 2; ++mt)
; #pragma unroll
;                     for (int g4 = 0; g4 < 4; ++g4) { const int i0 = 32 * mt + 8 * g4 + 4 * h;
;                         const f32x4 bv = *(const LAS f32x4*)(sc_beta + i0), ev = *(const LAS f32x4*)(sc_eg + i0);
; #pragma unroll
;                         for (int e = 0; e < 4; ++e) { const int x = 4 * g4 + e; KS[mt][x] = bv[e] * (bf2f(Vb[(i0 + e) * 128 + 32 * w + r]) - ev[e] * KS[mt][x]); } }
;                 bf16x8 Xp[4];
; #pragma unroll
;                 for (int ks = 0; ks < 4; ++ks) Xp[ks] = pack_step(KS[ks >> 1], ks & 1);
;                 f32x16 VN[2];
; #pragma unroll
;                 for (int mt = 0; mt < 2; ++mt) {
; #pragma unroll
;                     for (int x = 0; x < 16; ++x) VN[mt][x] = 0.f;
; #pragma unroll
;                     for (int ks = 0; ks < 4; ++ks) if (ks < 2 * mt + 2) VN[mt] = MFMA32(frag_perm(Tb, 72, 32 * mt + r, ks, h), Xp[ks], VN[mt]);
;                 }
;                 bf16x8 VNp[4];
; #pragma unroll
;                 for (int ks = 0; ks < 4; ++ks) VNp[ks] = pack_step(VN[ks >> 1], ks & 1);
; #pragma unroll
;                 for (int mt = 0; mt < 2; ++mt) {
; #pragma unroll
;                     for (int g4 = 0; g4 < 4; ++g4) { const f32x4 ev = *(const LAS f32x4*)(sc_eg + 32 * mt + 8 * g4 + 4 * h);
; #pragma unroll
;                         for (int e = 0; e < 4; ++e) QS[mt][4 * g4 + e] *= ev[e]; }
; #pragma unroll
;                     for (int ks = 0; ks < 4; ++ks) if (ks < 2 * mt + 2) QS[mt] = MFMA32(frag_perm(Ab, 72, 32 * mt + r, ks, h), VNp[ks], QS[mt]);
;                 }
; #pragma unroll
;                 for (int mt = 0; mt < 2; ++mt)
; #pragma unroll
;                     for (int x = 0; x < 16; ++x) Vb[(32 * mt + crow(x, h)) * 128 + 32 * w + r] = f2bf(QS[mt][x]);
; #pragma unroll
;                 for (int mt = 0; mt < 2; ++mt)
; #pragma unroll
;                     for (int g4 = 0; g4 < 4; ++g4) { const f32x4 tv = *(const LAS f32x4*)(sc_tail + 32 * mt + 8 * g4 + 4 * h);
; #pragma unroll
;                         for (int e = 0; e < 4; ++e) VN[mt][4 * g4 + e] *= tv[e]; }
; #pragma unroll
;                 for (int ks = 0; ks < 4; ++ks) VNp[ks] = pack_step(VN[ks >> 1], ks & 1);
	v_fma_f32 v126, -v78, v134, v126
	v_fma_f32 v127, -v79, v135, v127
	v_fma_f32 v128, -v80, v136, v128
	v_fma_f32 v129, -v81, v137, v129
	v_mul_f32_e32 v78, v130, v126
	v_mul_f32_e32 v79, v131, v127
	v_mul_f32_e32 v80, v132, v128
	v_mul_f32_e32 v81, v133, v129
	ds_read_u16 v114, v213 offset:43008
	ds_read_u16 v115, v213 offset:43264
	ds_read_u16 v116, v213 offset:43520
	ds_read_u16 v117, v213 offset:43776
	ds_read_b128 v[118:121], v214 offset:128
	ds_read_b128 v[122:125], v214 offset:640
	ds_read_b128 v[154:157], v212 offset:17568
	v_mfma_f32_32x32x16_bf16 v[82:97], v[158:161], v[242:245], v[82:97]
	v_cvt_pk_bf16_f32 v158, v74, v75
	v_cvt_pk_bf16_f32 v160, v78, v79
	v_cvt_pk_bf16_f32 v159, v76, v77
	v_cvt_pk_bf16_f32 v161, v80, v81
	v_permlane32_swap_b32_e32 v158, v160
	s_nop 0
	v_permlane32_swap_b32_e32 v159, v161
	ds_read_u16 v126, v213 offset:45056
	ds_read_u16 v127, v213 offset:45312
	ds_read_u16 v128, v213 offset:45568
	ds_read_u16 v129, v213 offset:45824
	ds_read_b128 v[130:133], v214 offset:160
	ds_read_b128 v[134:137], v214 offset:672
	v_mfma_f32_32x32x16_bf16 v[82:97], v[162:165], v[246:249], v[82:97]
	ds_read_b128 v[162:165], v212 offset:17600
	v_mfma_f32_32x32x16_bf16 v[98:113], v[166:169], v[218:221], 0
	ds_read_b128 v[166:169], v212 offset:17632
	v_mfma_f32_32x32x16_bf16 v[98:113], v[138:141], v[222:225], v[98:113]
	ds_read_b128 v[138:141], v212 offset:26112
	v_mfma_f32_32x32x16_bf16 v[98:113], v[170:173], v[226:229], v[98:113]
	v_lshlrev_b32_e32 v114, 16, v114
	s_waitcnt lgkmcnt(14)
	v_lshlrev_b32_e32 v115, 16, v115
	s_waitcnt lgkmcnt(13)
	v_lshlrev_b32_e32 v116, 16, v116
	s_waitcnt lgkmcnt(12)
	v_lshlrev_b32_e32 v117, 16, v117
	s_waitcnt lgkmcnt(10)
	v_fma_f32 v114, -v82, v122, v114
	v_fma_f32 v115, -v83, v123, v115
	v_fma_f32 v116, -v84, v124, v116
	v_fma_f32 v117, -v85, v125, v117
	v_mul_f32_e32 v82, v118, v114
	v_mul_f32_e32 v83, v119, v115
	v_mul_f32_e32 v84, v120, v116
	v_mul_f32_e32 v85, v121, v117
	ds_read_u16 v114, v213 offset:47104
	ds_read_u16 v115, v213 offset:47360
	ds_read_u16 v116, v213 offset:47616
	ds_read_u16 v117, v213 offset:47872
	ds_read_b128 v[118:121], v214 offset:192
	ds_read_b128 v[122:125], v214 offset:704
	ds_read_b128 v[170:173], v212 offset:26144
	v_mfma_f32_32x32x16_bf16 v[98:113], v[142:145], v[230:233], v[98:113]
	v_lshlrev_b32_e32 v126, 16, v126
	s_waitcnt lgkmcnt(14)
	v_lshlrev_b32_e32 v127, 16, v127
	s_waitcnt lgkmcnt(13)
	v_lshlrev_b32_e32 v128, 16, v128
	s_waitcnt lgkmcnt(12)
	v_lshlrev_b32_e32 v129, 16, v129
	s_waitcnt lgkmcnt(10)
	v_fma_f32 v126, -v86, v134, v126
	v_fma_f32 v127, -v87, v135, v127
	v_fma_f32 v128, -v88, v136, v128
	v_fma_f32 v129, -v89, v137, v129
	v_mul_f32_e32 v86, v130, v126
	v_mul_f32_e32 v87, v131, v127
	v_mul_f32_e32 v88, v132, v128
	v_mul_f32_e32 v89, v133, v129
	ds_read_u16 v126, v213 offset:49152
	ds_read_u16 v127, v213 offset:49408
	ds_read_u16 v128, v213 offset:49664
	ds_read_u16 v129, v213 offset:49920
	ds_read_b128 v[130:133], v214 offset:224
	ds_read_b128 v[134:137], v214 offset:736
	ds_read_b128 v[142:145], v212 offset:26176
	v_mfma_f32_32x32x16_bf16 v[98:113], v[146:149], v[234:237], v[98:113]
	v_cvt_pk_bf16_f32 v146, v82, v83
	v_cvt_pk_bf16_f32 v148, v86, v87
	v_cvt_pk_bf16_f32 v147, v84, v85
	v_cvt_pk_bf16_f32 v149, v88, v89
	v_permlane32_swap_b32_e32 v146, v148
	s_nop 0
	v_permlane32_swap_b32_e32 v147, v149
	s_waitcnt lgkmcnt(13)
	v_lshlrev_b32_e32 v114, 16, v114
	s_waitcnt lgkmcnt(12)
	v_lshlrev_b32_e32 v115, 16, v115
	s_waitcnt lgkmcnt(11)
	v_lshlrev_b32_e32 v116, 16, v116
	s_waitcnt lgkmcnt(10)
	v_lshlrev_b32_e32 v117, 16, v117
	s_waitcnt lgkmcnt(8)
	v_fma_f32 v114, -v90, v122, v114
	v_fma_f32 v115, -v91, v123, v115
	v_fma_f32 v116, -v92, v124, v116
	v_fma_f32 v117, -v93, v125, v117
	v_mul_f32_e32 v90, v118, v114
	v_mul_f32_e32 v91, v119, v115
	v_mul_f32_e32 v92, v120, v116
	v_mul_f32_e32 v93, v121, v117
	v_mfma_f32_32x32x16_bf16 v[98:113], v[154:157], v[238:241], v[98:113]
	s_waitcnt lgkmcnt(6)
	v_lshlrev_b32_e32 v126, 16, v126
	s_waitcnt lgkmcnt(5)
	v_lshlrev_b32_e32 v127, 16, v127
	s_waitcnt lgkmcnt(4)
	v_lshlrev_b32_e32 v128, 16, v128
	s_waitcnt lgkmcnt(3)
	v_lshlrev_b32_e32 v129, 16, v129
	s_waitcnt lgkmcnt(1)
	v_fma_f32 v126, -v94, v134, v126
	v_fma_f32 v127, -v95, v135, v127
	v_fma_f32 v128, -v96, v136, v128
	v_fma_f32 v129, -v97, v137, v129
	v_mul_f32_e32 v94, v130, v126
	v_mul_f32_e32 v95, v131, v127
	v_mul_f32_e32 v96, v132, v128
	v_mul_f32_e32 v97, v133, v129
	ds_read_b128 v[154:157], v212 offset:26208
	v_mfma_f32_32x32x16_bf16 v[98:113], v[162:165], v[242:245], v[98:113]
	v_cvt_pk_bf16_f32 v162, v90, v91
	v_cvt_pk_bf16_f32 v164, v94, v95
	v_cvt_pk_bf16_f32 v163, v92, v93
	v_cvt_pk_bf16_f32 v165, v96, v97
	v_permlane32_swap_b32_e32 v162, v164
	s_nop 0
	v_permlane32_swap_b32_e32 v163, v165
	v_mfma_f32_32x32x16_bf16 v[98:113], v[166:169], v[246:249], v[98:113]
	ds_read_b32 v130, v217
	ds_read_b128 v[134:137], v214 offset:512
	ds_read_b128 v[166:169], v212 offset:26240
	v_mfma_f32_32x32x16_bf16 v[114:129], v[138:141], v[218:221], 0
	s_waitcnt lgkmcnt(2)
	v_mul_f32_e32 v50, v50, v130
	v_mul_f32_e32 v51, v51, v130
	v_mul_f32_e32 v52, v52, v130
	v_mul_f32_e32 v53, v53, v130
	v_mul_f32_e32 v54, v54, v130
	v_mul_f32_e32 v55, v55, v130
	v_mul_f32_e32 v56, v56, v130
	v_mul_f32_e32 v57, v57, v130
	ds_read_b128 v[138:141], v214 offset:544
	v_mfma_f32_32x32x16_bf16 v[114:129], v[170:173], v[222:225], v[114:129]
	v_mul_f32_e32 v58, v58, v130
	v_mul_f32_e32 v59, v59, v130
	v_mul_f32_e32 v60, v60, v130
	v_mul_f32_e32 v61, v61, v130
	v_mul_f32_e32 v62, v62, v130
	v_mul_f32_e32 v63, v63, v130
	v_mul_f32_e32 v64, v64, v130
	v_mul_f32_e32 v65, v65, v130
	v_mul_f32_e32 v34, v34, v130
	v_mul_f32_e32 v35, v35, v130
	s_waitcnt lgkmcnt(2)
; __device__ __forceinline__ int crow(int r, int hi) { return (r & 3) + 8 * (r >> 2) + 4 * hi; }
; #define LAS __attribute__((address_space(3)))
; __device__ __forceinline__ bf16_t f2bf(float f) { return (bf16_t)(cvtpk_s(f, 0.f) & 0xffffu); }
; __device__ __forceinline__ int crow(int x, int h) { return (x & 3) + 8 * (x >> 2) + 4 * h; }
; #define MFMA32(a, b, c) __builtin_amdgcn_mfma_f32_32x32x16_bf16((a), (b), (c), 0, 0, 0)
; template <int VAR> __device__ __forceinline__ void dn_scan3(LAS unsigned char* lds, const bf16_t* P, const float* AB, const bf16_t* TP, bf16_t* OB) {
;     ...
;                 for (int mt = 0; mt < 2; ++mt) {
; #pragma unroll
;                     for (int x = 0; x < 16; ++x) VN[mt][x] = 0.f;
; #pragma unroll
;                     for (int ks = 0; ks < 4; ++ks) if (ks < 2 * mt + 2) VN[mt] = MFMA32(frag_perm(Tb, 72, 32 * mt + r, ks, h), Xp[ks], VN[mt]);
;                 }
;                 bf16x8 VNp[4];
; #pragma unroll
;                 for (int ks = 0; ks < 4; ++ks) VNp[ks] = pack_step(VN[ks >> 1], ks & 1);
; #pragma unroll
;                 for (int mt = 0; mt < 2; ++mt) {
; #pragma unroll
;                     for (int g4 = 0; g4 < 4; ++g4) { const f32x4 ev = *(const LAS f32x4*)(sc_eg + 32 * mt + 8 * g4 + 4 * h);
; #pragma unroll
;                         for (int e = 0; e < 4; ++e) QS[mt][4 * g4 + e] *= ev[e]; }
; #pragma unroll
;                     for (int ks = 0; ks < 4; ++ks) if (ks < 2 * mt + 2) QS[mt] = MFMA32(frag_perm(Ab, 72, 32 * mt + r, ks, h), VNp[ks], QS[mt]);
;                 }
; #pragma unroll
;                 for (int mt = 0; mt < 2; ++mt)
; #pragma unroll
;                     for (int x = 0; x < 16; ++x) Vb[(32 * mt + crow(x, h)) * 128 + 32 * w + r] = f2bf(QS[mt][x]);
; #pragma unroll
;                 for (int mt = 0; mt < 2; ++mt)
; #pragma unroll
;                     for (int g4 = 0; g4 < 4; ++g4) { const f32x4 tv = *(const LAS f32x4*)(sc_tail + 32 * mt + 8 * g4 + 4 * h);
; #pragma unroll
;                         for (int e = 0; e < 4; ++e) VN[mt][4 * g4 + e] *= tv[e]; }
; #pragma unroll
;                 for (int ks = 0; ks < 4; ++ks) VNp[ks] = pack_step(VN[ks >> 1], ks & 1);
	v_mul_f32_e32 v98, v98, v134
	v_mul_f32_e32 v99, v99, v135
	v_mul_f32_e32 v100, v100, v136
	v_mul_f32_e32 v101, v101, v137
	ds_read_b128 v[134:137], v214 offset:576
	ds_read_b128 v[170:173], v212 offset:26272
	v_mfma_f32_32x32x16_bf16 v[114:129], v[142:145], v[226:229], v[114:129]
	v_mul_f32_e32 v36, v36, v130
	v_mul_f32_e32 v37, v37, v130
	v_mul_f32_e32 v38, v38, v130
	v_mul_f32_e32 v39, v39, v130
	v_mul_f32_e32 v40, v40, v130
	v_mul_f32_e32 v41, v41, v130
	v_mul_f32_e32 v42, v42, v130
	v_mul_f32_e32 v43, v43, v130
	v_mul_f32_e32 v44, v44, v130
	v_mul_f32_e32 v45, v45, v130
	s_waitcnt lgkmcnt(2)
	v_mul_f32_e32 v102, v102, v138
	v_mul_f32_e32 v103, v103, v139
	v_mul_f32_e32 v104, v104, v140
	v_mul_f32_e32 v105, v105, v141
	ds_read_b128 v[138:141], v214 offset:608
	ds_read_b128 v[142:145], v212 offset:26304
	v_mfma_f32_32x32x16_bf16 v[114:129], v[154:157], v[230:233], v[114:129]
	v_mul_f32_e32 v46, v46, v130
	v_mul_f32_e32 v47, v47, v130
	v_mul_f32_e32 v48, v48, v130
	v_mul_f32_e32 v49, v49, v130
	v_mul_f32_e32 v18, v18, v130
	v_mul_f32_e32 v19, v19, v130
	v_mul_f32_e32 v20, v20, v130
	v_mul_f32_e32 v21, v21, v130
	v_mul_f32_e32 v22, v22, v130
	v_mul_f32_e32 v23, v23, v130
	s_waitcnt lgkmcnt(3)
	v_mul_f32_e32 v106, v106, v134
	v_mul_f32_e32 v107, v107, v135
	v_mul_f32_e32 v108, v108, v136
	v_mul_f32_e32 v109, v109, v137
	ds_read_b128 v[154:157], v212 offset:26336
	v_mfma_f32_32x32x16_bf16 v[114:129], v[166:169], v[234:237], v[114:129]
	v_mul_f32_e32 v24, v24, v130
	v_mul_f32_e32 v25, v25, v130
	v_mul_f32_e32 v26, v26, v130
	v_mul_f32_e32 v27, v27, v130
	v_mul_f32_e32 v28, v28, v130
	v_mul_f32_e32 v29, v29, v130
	v_mul_f32_e32 v30, v30, v130
	v_mul_f32_e32 v31, v31, v130
	v_mul_f32_e32 v32, v32, v130
	v_mul_f32_e32 v33, v33, v130
	s_waitcnt lgkmcnt(2)
	v_mul_f32_e32 v110, v110, v138
	v_mul_f32_e32 v111, v111, v139
	v_mul_f32_e32 v112, v112, v140
	v_mul_f32_e32 v113, v113, v141
	ds_read_b128 v[134:137], v215 offset:51200
	ds_read_b128 v[138:141], v215 offset:51232
	v_mfma_f32_32x32x16_bf16 v[114:129], v[170:173], v[238:241], v[114:129]
	v_mul_f32_e32 v2, v2, v130
	v_mul_f32_e32 v3, v3, v130
	v_mul_f32_e32 v4, v4, v130
	v_mul_f32_e32 v5, v5, v130
	v_mul_f32_e32 v6, v6, v130
	v_mul_f32_e32 v7, v7, v130
	v_mul_f32_e32 v8, v8, v130
	v_mul_f32_e32 v9, v9, v130
	ds_read_b128 v[166:169], v215 offset:55808
	ds_read_b128 v[170:173], v215 offset:55840
	s_waitcnt lgkmcnt(5)
	v_mfma_f32_32x32x16_bf16 v[114:129], v[142:145], v[242:245], v[114:129]
	v_mul_f32_e32 v10, v10, v130
	v_mul_f32_e32 v11, v11, v130
	v_mul_f32_e32 v12, v12, v130
	v_mul_f32_e32 v13, v13, v130
	v_mul_f32_e32 v14, v14, v130
	v_mul_f32_e32 v15, v15, v130
	v_mul_f32_e32 v16, v16, v130
	v_mul_f32_e32 v17, v17, v130
	ds_read_b128 v[142:145], v215 offset:55872
	ds_read_b128 v[174:177], v215 offset:55904
	s_waitcnt lgkmcnt(6)
	v_mfma_f32_32x32x16_bf16 v[114:129], v[154:157], v[246:249], v[114:129]
	ds_read_b128 v[130:133], v214 offset:640
	ds_read_b128 v[154:157], v214 offset:672
	s_waitcnt lgkmcnt(7)
	v_mfma_f32_32x32x16_bf16 v[66:81], v[134:137], v[150:153], 0
	ds_read_b128 v[134:137], v214 offset:704
	ds_read_b128 v[218:221], v214 offset:736
	s_waitcnt lgkmcnt(8)
	v_mfma_f32_32x32x16_bf16 v[66:81], v[138:141], v[158:161], v[66:81]
	ds_read_b128 v[138:141], v214 offset:768
	ds_read_b128 v[222:225], v214 offset:800
	s_waitcnt lgkmcnt(9)
	v_mfma_f32_32x32x16_bf16 v[82:97], v[166:169], v[150:153], 0
	ds_read_b128 v[150:153], v214 offset:832
	ds_read_b128 v[166:169], v214 offset:864
	s_waitcnt lgkmcnt(10)
	v_mfma_f32_32x32x16_bf16 v[82:97], v[170:173], v[158:161], v[82:97]
	s_waitcnt lgkmcnt(7)
	v_mul_f32_e32 v114, v114, v130
	v_mul_f32_e32 v115, v115, v131
	v_mul_f32_e32 v116, v116, v132
	v_mul_f32_e32 v117, v117, v133
	s_waitcnt lgkmcnt(6)
	v_mul_f32_e32 v118, v118, v154
	v_mul_f32_e32 v119, v119, v155
	v_mul_f32_e32 v120, v120, v156
	v_mul_f32_e32 v121, v121, v157
	ds_read_b128 v[130:133], v215 offset:60416
	ds_read_b128 v[154:157], v215 offset:60448
	v_mfma_f32_32x32x16_bf16 v[82:97], v[142:145], v[146:149], v[82:97]
	s_waitcnt lgkmcnt(7)
	v_mul_f32_e32 v122, v122, v134
	v_mul_f32_e32 v123, v123, v135
	v_mul_f32_e32 v124, v124, v136
	v_mul_f32_e32 v125, v125, v137
	s_waitcnt lgkmcnt(6)
	v_mul_f32_e32 v126, v126, v218
	v_mul_f32_e32 v127, v127, v219
	v_mul_f32_e32 v128, v128, v220
	v_mul_f32_e32 v129, v129, v221
	v_mfma_f32_32x32x16_bf16 v[82:97], v[174:177], v[162:165], v[82:97]
	v_add_u32_e32 v134, s41, v211
	v_add_u32_e32 v135, s41, v201
	v_and_b32_e32 v136, 0xffff, v180
	v_lshrrev_b32_e32 v137, 16, v180
	v_add_u32_e32 v136, s41, v136
	v_add_u32_e32 v137, s41, v137
	ds_read_b64_tr_b16 v[158:159], v134 offset:0
	ds_read_b64_tr_b16 v[160:161], v135 offset:0
	ds_read_b64_tr_b16 v[162:163], v134 offset:64
	ds_read_b64_tr_b16 v[164:165], v135 offset:64
	v_cvt_pk_bf16_f32 v142, v66, v67
	v_cvt_pk_bf16_f32 v144, v70, v71
	v_cvt_pk_bf16_f32 v143, v68, v69
	v_cvt_pk_bf16_f32 v145, v72, v73
	v_cvt_pk_bf16_f32 v146, v74, v75
	v_cvt_pk_bf16_f32 v148, v78, v79
	v_cvt_pk_bf16_f32 v147, v76, v77
	v_cvt_pk_bf16_f32 v149, v80, v81
	v_permlane32_swap_b32_e32 v142, v144
	v_permlane32_swap_b32_e32 v143, v145
	v_permlane32_swap_b32_e32 v146, v148
	v_permlane32_swap_b32_e32 v147, v149
	s_waitcnt lgkmcnt(9)
	v_mul_f32_e32 v66, v66, v138
	v_mul_f32_e32 v67, v67, v139
	v_mul_f32_e32 v68, v68, v140
	v_mul_f32_e32 v69, v69, v141
	s_waitcnt lgkmcnt(8)
	v_mul_f32_e32 v70, v70, v222
	v_mul_f32_e32 v71, v71, v223
	v_mul_f32_e32 v72, v72, v224
	v_mul_f32_e32 v73, v73, v225
	s_waitcnt lgkmcnt(7)
	v_mul_f32_e32 v74, v74, v150
	v_mul_f32_e32 v75, v75, v151
	v_mul_f32_e32 v76, v76, v152
	v_mul_f32_e32 v77, v77, v153
	s_waitcnt lgkmcnt(6)
; __device__ __forceinline__ int crow(int r, int hi) { return (r & 3) + 8 * (r >> 2) + 4 * hi; }
; #define LAS __attribute__((address_space(3)))
; __device__ __forceinline__ bf16_t f2bf(float f) { return (bf16_t)(cvtpk_s(f, 0.f) & 0xffffu); }
; __device__ __forceinline__ int crow(int x, int h) { return (x & 3) + 8 * (x >> 2) + 4 * h; }
; #define MFMA32(a, b, c) __builtin_amdgcn_mfma_f32_32x32x16_bf16((a), (b), (c), 0, 0, 0)
; template <int VAR> __device__ __forceinline__ void dn_scan3(LAS unsigned char* lds, const bf16_t* P, const float* AB, const bf16_t* TP, bf16_t* OB) {
;     ...
;                     for (int ks = 0; ks < 4; ++ks) if (ks < 2 * mt + 2) QS[mt] = MFMA32(frag_perm(Ab, 72, 32 * mt + r, ks, h), VNp[ks], QS[mt]);
;                 }
; #pragma unroll
;                 for (int mt = 0; mt < 2; ++mt)
; #pragma unroll
;                     for (int x = 0; x < 16; ++x) Vb[(32 * mt + crow(x, h)) * 128 + 32 * w + r] = f2bf(QS[mt][x]);
; #pragma unroll
;                 for (int mt = 0; mt < 2; ++mt)
; #pragma unroll
;                     for (int g4 = 0; g4 < 4; ++g4) { const f32x4 tv = *(const LAS f32x4*)(sc_tail + 32 * mt + 8 * g4 + 4 * h);
; #pragma unroll
;                         for (int e = 0; e < 4; ++e) VN[mt][4 * g4 + e] *= tv[e]; }
; #pragma unroll
;                 for (int ks = 0; ks < 4; ++ks) VNp[ks] = pack_step(VN[ks >> 1], ks & 1);
;                 const float dl = sc_dl[0];
; #pragma unroll
;                 for (int kt = 0; kt < 4; ++kt)
; #pragma unroll
;                     for (int x = 0; x < 16; ++x) S[kt][x] *= dl;
; #pragma unroll
;                 for (int ks = 0; ks < 4; ++ks) {
; #pragma unroll
;                     for (int kt = 0; kt < 4; ++kt) S[kt] = MFMA32(frag_tr(Kb, 136, 32 * kt, ks, lane), VNp[ks], S[kt]);
	v_mul_f32_e32 v78, v78, v166
	v_mul_f32_e32 v79, v79, v167
	v_mul_f32_e32 v80, v80, v168
	v_mul_f32_e32 v81, v81, v169
	v_cvt_pk_bf16_f32 v138, v66, v71
	v_cvt_pk_bf16_f32 v139, v76, v81
	v_cvt_pk_bf16_f32 v140, v67, v72
	v_cvt_pk_bf16_f32 v141, v77, v78
	v_cvt_pk_bf16_f32 v150, v68, v73
	v_cvt_pk_bf16_f32 v151, v74, v79
	v_cvt_pk_bf16_f32 v152, v69, v70
	v_cvt_pk_bf16_f32 v153, v75, v80
	ds_read_b64_tr_b16 v[166:167], v134 offset:128
	ds_read_b64_tr_b16 v[168:169], v135 offset:128
	ds_read_b64_tr_b16 v[170:171], v134 offset:192
	ds_read_b64_tr_b16 v[172:173], v135 offset:192
	ds_read_b64_tr_b16 v[174:175], v136 offset:0
	ds_read_b64_tr_b16 v[176:177], v137 offset:0
	ds_read_b64_tr_b16 v[218:219], v136 offset:64
	ds_read_b64_tr_b16 v[220:221], v137 offset:64
	s_waitcnt lgkmcnt(13)
	v_mfma_f32_32x32x16_bf16 v[98:113], v[130:133], v[142:145], v[98:113]
	ds_read_b128 v[130:133], v215 offset:65024
	ds_read_b128 v[222:225], v215 offset:65056
	s_waitcnt lgkmcnt(14)
	v_mfma_f32_32x32x16_bf16 v[98:113], v[154:157], v[146:149], v[98:113]
	ds_read_b128 v[154:157], v214 offset:896
	ds_read_b128 v[226:229], v214 offset:928
	ds_read_b64_tr_b16 v[230:231], v136 offset:128
	ds_read_b64_tr_b16 v[232:233], v137 offset:128
	ds_read_b64_tr_b16 v[234:235], v136 offset:192
	ds_read_b64_tr_b16 v[236:237], v137 offset:192
	ds_read_b64_tr_b16 v[238:239], v134 offset:8704
	ds_read_b64_tr_b16 v[240:241], v135 offset:8704
	v_mfma_f32_32x32x16_bf16 v[50:65], v[158:161], v[138:141], v[50:65]
	ds_read_b128 v[158:161], v214 offset:960
	ds_read_b128 v[242:245], v214 offset:992
	v_mfma_f32_32x32x16_bf16 v[34:49], v[162:165], v[138:141], v[34:49]
	v_cvt_pk_bf16_f32 v162, v82, v83
	v_cvt_pk_bf16_f32 v164, v86, v87
	v_cvt_pk_bf16_f32 v163, v84, v85
	v_cvt_pk_bf16_f32 v165, v88, v89
	v_permlane32_swap_b32_e32 v162, v164
	s_nop 0
	v_permlane32_swap_b32_e32 v163, v165
	v_mfma_f32_32x32x16_bf16 v[18:33], v[166:169], v[138:141], v[18:33]
	v_cvt_pk_bf16_f32 v166, v90, v91
	v_cvt_pk_bf16_f32 v168, v94, v95
	v_cvt_pk_bf16_f32 v167, v92, v93
	v_cvt_pk_bf16_f32 v169, v96, v97
	v_permlane32_swap_b32_e32 v166, v168
	s_nop 0
	v_permlane32_swap_b32_e32 v167, v169
	v_mfma_f32_32x32x16_bf16 v[2:17], v[170:173], v[138:141], v[2:17]
	s_waitcnt lgkmcnt(9)
	v_mul_f32_e32 v82, v82, v154
	v_mul_f32_e32 v83, v83, v155
	v_mul_f32_e32 v84, v84, v156
	v_mul_f32_e32 v85, v85, v157
	s_waitcnt lgkmcnt(8)
	v_mul_f32_e32 v86, v86, v226
	v_mul_f32_e32 v87, v87, v227
	v_mul_f32_e32 v88, v88, v228
	v_mul_f32_e32 v89, v89, v229
	ds_read_b128 v[154:157], v215 offset:65088
	ds_read_b128 v[170:173], v215 offset:65120
	v_mfma_f32_32x32x16_bf16 v[50:65], v[174:177], v[150:153], v[50:65]
	v_cvt_pk_bf16_f32 v174, v98, s0
	ds_write_b16 v213, v174 offset:34816
	v_cvt_pk_bf16_f32 v175, v99, s0
	ds_write_b16 v213, v175 offset:35072
	s_waitcnt lgkmcnt(5)
	v_mul_f32_e32 v90, v90, v158
	v_mul_f32_e32 v91, v91, v159
	v_mul_f32_e32 v92, v92, v160
	v_mul_f32_e32 v93, v93, v161
	s_waitcnt lgkmcnt(4)
	v_mul_f32_e32 v94, v94, v242
	v_mul_f32_e32 v95, v95, v243
	v_mul_f32_e32 v96, v96, v244
	v_mul_f32_e32 v97, v97, v245
	ds_read_b64_tr_b16 v[158:159], v134 offset:8768
	ds_read_b64_tr_b16 v[160:161], v135 offset:8768
	v_mfma_f32_32x32x16_bf16 v[34:49], v[218:221], v[150:153], v[34:49]
	v_cvt_pk_bf16_f32 v176, v100, s0
	ds_write_b16 v213, v176 offset:35328
	v_cvt_pk_bf16_f32 v177, v101, s0
	ds_write_b16 v213, v177 offset:35584
	v_cvt_pk_bf16_f32 v218, v82, v87
	v_cvt_pk_bf16_f32 v219, v92, v97
	v_cvt_pk_bf16_f32 v220, v83, v88
	v_cvt_pk_bf16_f32 v221, v93, v94
	ds_read_b64_tr_b16 v[226:227], v134 offset:8832
	ds_read_b64_tr_b16 v[228:229], v135 offset:8832
	v_mfma_f32_32x32x16_bf16 v[18:33], v[230:233], v[150:153], v[18:33]
	v_cvt_pk_bf16_f32 v174, v102, s0
	ds_write_b16 v213, v174 offset:36864
	v_cvt_pk_bf16_f32 v175, v103, s0
	ds_write_b16 v213, v175 offset:37120
	v_cvt_pk_bf16_f32 v230, v84, v89
	v_cvt_pk_bf16_f32 v231, v90, v95
	v_cvt_pk_bf16_f32 v232, v85, v86
	v_cvt_pk_bf16_f32 v233, v91, v96
	v_mfma_f32_32x32x16_bf16 v[2:17], v[234:237], v[150:153], v[2:17]
	v_cvt_pk_bf16_f32 v176, v104, s0
	ds_write_b16 v213, v176 offset:37376
	v_cvt_pk_bf16_f32 v177, v105, s0
	ds_write_b16 v213, v177 offset:37632
	v_mfma_f32_32x32x16_bf16 v[114:129], v[130:133], v[142:145], v[114:129]
	v_cvt_pk_bf16_f32 v174, v106, s0
	ds_write_b16 v213, v174 offset:38912
	v_cvt_pk_bf16_f32 v175, v107, s0
	ds_write_b16 v213, v175 offset:39168
	ds_read_b64_tr_b16 v[130:131], v134 offset:8896
	ds_read_b64_tr_b16 v[132:133], v135 offset:8896
	ds_read_b64_tr_b16 v[138:139], v136 offset:8704
	ds_read_b64_tr_b16 v[140:141], v137 offset:8704
	v_mfma_f32_32x32x16_bf16 v[114:129], v[222:225], v[146:149], v[114:129]
	v_cvt_pk_bf16_f32 v176, v108, s0
	ds_write_b16 v213, v176 offset:39424
	v_cvt_pk_bf16_f32 v177, v109, s0
	ds_write_b16 v213, v177 offset:39680
	ds_read_b64_tr_b16 v[142:143], v136 offset:8768
	ds_read_b64_tr_b16 v[144:145], v137 offset:8768
	ds_read_b64_tr_b16 v[146:147], v136 offset:8832
	ds_read_b64_tr_b16 v[148:149], v137 offset:8832
	v_mfma_f32_32x32x16_bf16 v[114:129], v[154:157], v[162:165], v[114:129]
	v_cvt_pk_bf16_f32 v174, v110, s0
	ds_write_b16 v213, v174 offset:40960
	v_cvt_pk_bf16_f32 v175, v111, s0
	ds_write_b16 v213, v175 offset:41216
	ds_read_b64_tr_b16 v[150:151], v136 offset:8896
	ds_read_b64_tr_b16 v[152:153], v137 offset:8896
	v_mfma_f32_32x32x16_bf16 v[114:129], v[170:173], v[166:169], v[114:129]
	v_cvt_pk_bf16_f32 v176, v112, s0
	ds_write_b16 v213, v176 offset:41472
	v_cvt_pk_bf16_f32 v177, v113, s0
	ds_write_b16 v213, v177 offset:41728
	ds_read_b32 v154, v179 offset:34816
	ds_read_b32 v155, v179 offset:35840
	ds_read_b32 v156, v179 offset:36864
	ds_read_b32 v157, v179 offset:37888
	ds_read_b32 v162, v179 offset:38912
	ds_read_b32 v163, v179 offset:39936
	ds_read_b32 v164, v179 offset:40960
	ds_read_b32 v165, v179 offset:41984
	v_mfma_f32_32x32x16_bf16 v[50:65], v[238:241], v[218:221], v[50:65]
	v_cvt_pk_bf16_f32 v174, v114, s0
	ds_write_b16 v213, v174 offset:43008
	v_cvt_pk_bf16_f32 v175, v115, s0
	ds_write_b16 v213, v175 offset:43264
	v_cvt_pk_bf16_f32 v176, v116, s0
	ds_write_b16 v213, v176 offset:43520
	v_cvt_pk_bf16_f32 v177, v117, s0
	ds_write_b16 v213, v177 offset:43776
	v_add_u32_e32 v195, s60, v194
	s_waitcnt lgkmcnt(11)
; __device__ __forceinline__ int opaque_tid() { int t = threadIdx.x; asm volatile("" : "+v"(t)); return t; }
; #define LAS __attribute__((address_space(3)))
; template <int VAR> __device__ __forceinline__ void dn_scan3(LAS unsigned char* lds, const bf16_t* P, const float* AB, const bf16_t* TP, bf16_t* OB) {
;     ...
;             if (w < 3) {
;                 const int qh = w >= 1 ? 1 : 0, khh = w == 2 ? 1 : 0, ti = qh, tj = khh;
;                 u32x4 q8[8], k8[8]; float gcp;
;                 {
;                     int rb; bool f_; dn_step_rb(0, dir, b, rb, f_);
;                     const int lane = opaque_tid() & 63, r0 = lane >> 4, c8 = 8 * (lane & 15);
; #pragma unroll
;                     for (int v = 0; v < 8; ++v) { const int ipq = 32 * qh + r0 + 4 * v, ipk = 32 * khh + r0 + 4 * v, iq = dir ? 63 - ipq : ipq, ik = dir ? 63 - ipk : ipk;
;                         q8[v] = *(const u32x4*)(P + (size_t)(rb * 64 + iq) * 4096 + kh * 128 + c8); k8[v] = *(const u32x4*)(P + (size_t)(rb * 64 + ik) * 4096 + 1024 + kh * 128 + c8); }
;                     const int tl = dir ? 63 - lane : lane; gcp = AB[(size_t)(rb * 64 + tl) * 64 + dir * 16 + vh];
;     ...
;                         for (int v = 0; v < 16; ++v) { const int ip_ = r0 + 4 * v, i_ = dir ? 63 - ip_ : ip_;
;                             atomic_add_bf16x8(OB + (size_t)(rbo * 64 + i_) * 2048 + vh * 128 + c8, *(const LAS u32x4*)(Vb + ip_ * 128 + c8)); }
	global_atomic_pk_add_bf16 v195, v154, s[42:43]
	v_add_u32_e32 v200, s61, v194
	s_waitcnt lgkmcnt(10)
	global_atomic_pk_add_bf16 v200, v155, s[42:43]
	v_mfma_f32_32x32x16_bf16 v[34:49], v[158:161], v[218:221], v[34:49]
	v_cvt_pk_bf16_f32 v174, v118, s0
	ds_write_b16 v213, v174 offset:45056
	v_cvt_pk_bf16_f32 v175, v119, s0
	ds_write_b16 v213, v175 offset:45312
	v_cvt_pk_bf16_f32 v176, v120, s0
	ds_write_b16 v213, v176 offset:45568
	v_cvt_pk_bf16_f32 v177, v121, s0
	ds_write_b16 v213, v177 offset:45824
	v_add_u32_e32 v195, s62, v195
	s_waitcnt lgkmcnt(13)
	global_atomic_pk_add_bf16 v195, v156, s[42:43]
	v_add_u32_e32 v200, s62, v200
	s_waitcnt lgkmcnt(12)
	global_atomic_pk_add_bf16 v200, v157, s[42:43]
	v_mfma_f32_32x32x16_bf16 v[18:33], v[226:229], v[218:221], v[18:33]
	v_cvt_pk_bf16_f32 v174, v122, s0
	ds_write_b16 v213, v174 offset:47104
	v_cvt_pk_bf16_f32 v175, v123, s0
	ds_write_b16 v213, v175 offset:47360
	v_cvt_pk_bf16_f32 v176, v124, s0
	ds_write_b16 v213, v176 offset:47616
	v_cvt_pk_bf16_f32 v177, v125, s0
	ds_write_b16 v213, v177 offset:47872
	v_add_u32_e32 v195, s62, v195
	global_atomic_pk_add_bf16 v195, v162, s[42:43]
	v_add_u32_e32 v200, s62, v200
	s_waitcnt lgkmcnt(14)
	global_atomic_pk_add_bf16 v200, v163, s[42:43]
	v_mfma_f32_32x32x16_bf16 v[2:17], v[130:133], v[218:221], v[2:17]
	v_cvt_pk_bf16_f32 v174, v126, s0
	ds_write_b16 v213, v174 offset:49152
	v_cvt_pk_bf16_f32 v175, v127, s0
	ds_write_b16 v213, v175 offset:49408
	v_cvt_pk_bf16_f32 v176, v128, s0
	ds_write_b16 v213, v176 offset:49664
	v_cvt_pk_bf16_f32 v177, v129, s0
	ds_write_b16 v213, v177 offset:49920
	v_add_u32_e32 v195, s62, v195
	global_atomic_pk_add_bf16 v195, v164, s[42:43]
	v_add_u32_e32 v200, s62, v200
	global_atomic_pk_add_bf16 v200, v165, s[42:43]
	v_mfma_f32_32x32x16_bf16 v[50:65], v[138:141], v[230:233], v[50:65]
	ds_read_b32 v130, v179 offset:43008
	ds_read_b32 v131, v179 offset:44032
	ds_read_b32 v132, v179 offset:45056
	ds_read_b32 v133, v179 offset:46080
	ds_read_b32 v138, v179 offset:47104
	ds_read_b32 v139, v179 offset:48128
	ds_read_b32 v140, v179 offset:49152
	ds_read_b32 v141, v179 offset:50176
	v_mfma_f32_32x32x16_bf16 v[34:49], v[142:145], v[230:233], v[34:49]
	v_add_u32_e32 v195, s62, v195
	s_waitcnt lgkmcnt(7)
	global_atomic_pk_add_bf16 v195, v130, s[42:43]
	v_add_u32_e32 v200, s62, v200
	s_waitcnt lgkmcnt(6)
	global_atomic_pk_add_bf16 v200, v131, s[42:43]
	v_mfma_f32_32x32x16_bf16 v[18:33], v[146:149], v[230:233], v[18:33]
	v_add_u32_e32 v195, s62, v195
	s_waitcnt lgkmcnt(5)
	global_atomic_pk_add_bf16 v195, v132, s[42:43]
	v_add_u32_e32 v200, s62, v200
	s_waitcnt lgkmcnt(4)
	global_atomic_pk_add_bf16 v200, v133, s[42:43]
	v_mfma_f32_32x32x16_bf16 v[2:17], v[150:153], v[230:233], v[2:17]
	v_add_u32_e32 v195, s62, v195
	s_waitcnt lgkmcnt(3)
	global_atomic_pk_add_bf16 v195, v138, s[42:43]
	v_add_u32_e32 v200, s62, v200
	s_waitcnt lgkmcnt(2)
	global_atomic_pk_add_bf16 v200, v139, s[42:43]
	v_add_u32_e32 v195, s62, v195
	s_waitcnt lgkmcnt(1)
	global_atomic_pk_add_bf16 v195, v140, s[42:43]
	v_add_u32_e32 v200, s62, v200
	s_waitcnt lgkmcnt(0)
	global_atomic_pk_add_bf16 v200, v141, s[42:43]
	s_waitcnt lgkmcnt(0)
	s_barrier
	s_add_i32 s40, s40, 1
	s_cmpk_lg_i32 s40, 0x104
	s_cbranch_scc1 .LBB0_377
.Ldn_state_done:
	s_mov_b64 s[40:41], 0
.LBB0_379:
	s_and_b64 vcc, exec, s[40:41]
	s_cbranch_vccz .LBB0_374
	s_ashr_i32 s56, s54, 5
	s_bfe_u32 s57, s54, 0x40001
	s_and_b32 s58, s54, 1
	s_bfe_i32 s42, s54, 0x10000
	s_cmp_eq_u32 s58, 0
	s_cselect_b64 s[40:41], -1, 0
	s_lshl_b32 s55, s56, 2
	s_and_b32 s42, s42, 3
	s_addk_i32 s55, 0x200
	s_or_b32 s59, s55, s42
	s_andn2_b64 vcc, exec, s[10:11]
	s_mov_b64 s[42:43], -1
	s_cbranch_vccnz .LBB0_448
	v_mov_b32_e32 v8, v188
	s_lshl_b32 s44, s59, 6
	v_bfe_u32 v10, v8, 4, 2
	v_or_b32_e32 v12, s52, v10
	v_bitop3_b32 v5, v10, 63, s52 bitop3:0x36
	v_cndmask_b32_e64 v6, v5, v12, s[40:41]
	v_or_b32_e32 v11, s19, v10
	s_lshl_b32 s42, s57, 7
	v_bitop3_b32 v4, v10, 63, s19 bitop3:0x36
	v_or_b32_e32 v6, s44, v6
	s_and_b32 s80, s42, 0x700
	v_cndmask_b32_e64 v4, v4, v11, s[40:41]
	v_ashrrev_i32_e32 v7, 31, v6
	s_add_u32 s42, s96, s80
	v_lshlrev_b32_e32 v0, 4, v8
	v_or_b32_e32 v4, s44, v4
	v_lshlrev_b64 v[6:7], 13, v[6:7]
	s_addc_u32 s43, s97, 0
	v_and_b32_e32 v0, 0xf0, v0
	v_ashrrev_i32_e32 v5, 31, v4
	v_lshl_add_u64 v[6:7], s[96:97], 0, v[6:7]
	v_lshl_add_u64 v[2:3], s[42:43], 0, v[0:1]
	v_lshlrev_b64 v[4:5], 13, v[4:5]
	v_lshl_add_u64 v[6:7], v[6:7], 0, s[80:81]
	v_lshl_add_u64 v[4:5], v[2:3], 0, v[4:5]
	v_lshl_add_u64 v[6:7], v[6:7], 0, v[0:1]
	global_load_dwordx4 v[22:25], v[4:5], off
	global_load_dwordx4 v[18:21], v[6:7], off offset:2048
	v_or_b32_e32 v4, 4, v11
	v_bitop3_b32 v6, v10, 59, s19 bitop3:0x36
	v_or_b32_e32 v5, 4, v12
	v_cndmask_b32_e64 v4, v6, v4, s[40:41]
	v_bitop3_b32 v6, v10, 59, s52 bitop3:0x36
	v_cndmask_b32_e64 v6, v6, v5, s[40:41]
	v_or_b32_e32 v6, s44, v6
	v_ashrrev_i32_e32 v7, 31, v6
	v_or_b32_e32 v4, s44, v4
	v_lshlrev_b64 v[6:7], 13, v[6:7]
	v_ashrrev_i32_e32 v5, 31, v4
	v_lshl_add_u64 v[6:7], s[96:97], 0, v[6:7]
	v_lshlrev_b64 v[4:5], 13, v[4:5]
	v_lshl_add_u64 v[6:7], v[6:7], 0, s[80:81]
	v_lshl_add_u64 v[4:5], v[2:3], 0, v[4:5]
	v_lshl_add_u64 v[6:7], v[6:7], 0, v[0:1]
	global_load_dwordx4 v[26:29], v[4:5], off
	global_load_dwordx4 v[30:33], v[6:7], off offset:2048
	v_or_b32_e32 v4, 8, v11
	v_bitop3_b32 v6, v10, 55, s19 bitop3:0x36
	v_or_b32_e32 v5, 8, v12
	v_cndmask_b32_e64 v4, v6, v4, s[40:41]
	v_bitop3_b32 v6, v10, 55, s52 bitop3:0x36
	v_cndmask_b32_e64 v6, v6, v5, s[40:41]
	v_or_b32_e32 v6, s44, v6
	v_ashrrev_i32_e32 v7, 31, v6
	v_or_b32_e32 v4, s44, v4
	v_lshlrev_b64 v[6:7], 13, v[6:7]
; __device__ __forceinline__ int opaque_tid() { int t = threadIdx.x; asm volatile("" : "+v"(t)); return t; }
; #define LAS __attribute__((address_space(3)))
; template <int VAR> __device__ __forceinline__ void dn_scan3(LAS unsigned char* lds, const bf16_t* P, const float* AB, const bf16_t* TP, bf16_t* OB) {
;     ...
;                     for (int v = 0; v < 8; ++v) { const int ipq = 32 * qh + r0 + 4 * v, ipk = 32 * khh + r0 + 4 * v, iq = dir ? 63 - ipq : ipq, ik = dir ? 63 - ipk : ipk;
;                         q8[v] = *(const u32x4*)(P + (size_t)(rb * 64 + iq) * 4096 + kh * 128 + c8); k8[v] = *(const u32x4*)(P + (size_t)(rb * 64 + ik) * 4096 + 1024 + kh * 128 + c8); }
;                     const int tl = dir ? 63 - lane : lane; gcp = AB[(size_t)(rb * 64 + tl) * 64 + dir * 16 + vh];
;                 }
;                 for (int j = 0; j < 260; ++j) {
;                     const int lane = opaque_tid() & 63, r = lane & 31, h = lane >> 5, r0 = lane >> 4, c8 = 8 * (lane & 15);
;                     LAS unsigned char* base = lds + (j & 1) * DN_DIR;
;                     LAS bf16_t* Kb = (LAS bf16_t*)(base + DN_KB); LAS bf16_t* Qb = (LAS bf16_t*)(base + DN_QB); LAS bf16_t* Ab = (LAS bf16_t*)(base + DN_AB);
;                     LAS float* hgc = (LAS float*)(lds + DN3_HGC + w * 256);
; #pragma unroll
;                     for (int v = 0; v < 8; ++v) { *(LAS u32x4*)(Qb + (32 * qh + r0 + 4 * v) * 136 + c8) = q8[v]; *(LAS u32x4*)(Kb + (32 * khh + r0 + 4 * v) * 136 + c8) = k8[v]; }
;                     hgc[lane] = gcp;
;                     asm volatile("s_waitcnt lgkmcnt(0)" ::: "memory");
;                     if (j + 1 < 260) {
;                         int rb; bool f_; dn_step_rb(j + 1, dir, b, rb, f_);
; #pragma unroll
;                         for (int v = 0; v < 8; ++v) { const int ipq = 32 * qh + r0 + 4 * v, ipk = 32 * khh + r0 + 4 * v, iq = dir ? 63 - ipq : ipq, ik = dir ? 63 - ipk : ipk;
;                             q8[v] = *(const u32x4*)(P + (size_t)(rb * 64 + iq) * 4096 + kh * 128 + c8); k8[v] = *(const u32x4*)(P + (size_t)(rb * 64 + ik) * 4096 + 1024 + kh * 128 + c8); }
;                         const int tl = dir ? 63 - lane : lane; gcp = AB[(size_t)(rb * 64 + tl) * 64 + dir * 16 + vh];
	v_ashrrev_i32_e32 v5, 31, v4
	v_lshl_add_u64 v[6:7], s[96:97], 0, v[6:7]
	v_lshlrev_b64 v[4:5], 13, v[4:5]
	v_lshl_add_u64 v[6:7], v[6:7], 0, s[80:81]
	v_lshl_add_u64 v[4:5], v[2:3], 0, v[4:5]
	v_lshl_add_u64 v[6:7], v[6:7], 0, v[0:1]
	global_load_dwordx4 v[34:37], v[4:5], off
	global_load_dwordx4 v[38:41], v[6:7], off offset:2048
	v_or_b32_e32 v4, 12, v11
	v_bitop3_b32 v6, v10, 51, s19 bitop3:0x36
	v_or_b32_e32 v5, 12, v12
	v_cndmask_b32_e64 v4, v6, v4, s[40:41]
	v_bitop3_b32 v6, v10, 51, s52 bitop3:0x36
	v_cndmask_b32_e64 v6, v6, v5, s[40:41]
	v_or_b32_e32 v6, s44, v6
	v_ashrrev_i32_e32 v7, 31, v6
	v_or_b32_e32 v4, s44, v4
	v_lshlrev_b64 v[6:7], 13, v[6:7]
	v_ashrrev_i32_e32 v5, 31, v4
	v_lshl_add_u64 v[6:7], s[96:97], 0, v[6:7]
	v_lshlrev_b64 v[4:5], 13, v[4:5]
	v_lshl_add_u64 v[6:7], v[6:7], 0, s[80:81]
	v_lshl_add_u64 v[4:5], v[2:3], 0, v[4:5]
	v_lshl_add_u64 v[6:7], v[6:7], 0, v[0:1]
	global_load_dwordx4 v[42:45], v[4:5], off
	global_load_dwordx4 v[46:49], v[6:7], off offset:2048
	v_or_b32_e32 v4, 16, v11
	v_bitop3_b32 v6, v10, 47, s19 bitop3:0x36
	v_or_b32_e32 v5, 16, v12
	v_cndmask_b32_e64 v4, v6, v4, s[40:41]
	v_bitop3_b32 v6, v10, 47, s52 bitop3:0x36
	v_cndmask_b32_e64 v6, v6, v5, s[40:41]
	v_or_b32_e32 v6, s44, v6
	v_ashrrev_i32_e32 v7, 31, v6
	v_or_b32_e32 v4, s44, v4
	v_lshlrev_b64 v[6:7], 13, v[6:7]
	v_ashrrev_i32_e32 v5, 31, v4
	v_lshl_add_u64 v[6:7], s[96:97], 0, v[6:7]
	v_lshlrev_b64 v[4:5], 13, v[4:5]
	v_lshl_add_u64 v[6:7], v[6:7], 0, s[80:81]
	v_lshl_add_u64 v[4:5], v[2:3], 0, v[4:5]
	v_lshl_add_u64 v[6:7], v[6:7], 0, v[0:1]
	global_load_dwordx4 v[54:57], v[4:5], off
	global_load_dwordx4 v[50:53], v[6:7], off offset:2048
	v_or_b32_e32 v4, 20, v11
	v_bitop3_b32 v6, v10, 43, s19 bitop3:0x36
	v_or_b32_e32 v5, 20, v12
	v_cndmask_b32_e64 v4, v6, v4, s[40:41]
	v_bitop3_b32 v6, v10, 43, s52 bitop3:0x36
	v_cndmask_b32_e64 v6, v6, v5, s[40:41]
	v_or_b32_e32 v6, s44, v6
	v_ashrrev_i32_e32 v7, 31, v6
	v_or_b32_e32 v4, s44, v4
	v_lshlrev_b64 v[6:7], 13, v[6:7]
	v_ashrrev_i32_e32 v5, 31, v4
	v_lshl_add_u64 v[6:7], s[96:97], 0, v[6:7]
	v_lshlrev_b64 v[4:5], 13, v[4:5]
	v_lshl_add_u64 v[6:7], v[6:7], 0, s[80:81]
	v_lshl_add_u64 v[4:5], v[2:3], 0, v[4:5]
	v_lshl_add_u64 v[6:7], v[6:7], 0, v[0:1]
	global_load_dwordx4 v[62:65], v[4:5], off
	global_load_dwordx4 v[58:61], v[6:7], off offset:2048
	v_or_b32_e32 v4, 24, v11
	v_bitop3_b32 v6, v10, 39, s19 bitop3:0x36
	v_or_b32_e32 v5, 24, v12
	v_cndmask_b32_e64 v4, v6, v4, s[40:41]
	v_bitop3_b32 v6, v10, 39, s52 bitop3:0x36
	v_cndmask_b32_e64 v6, v6, v5, s[40:41]
	v_or_b32_e32 v6, s44, v6
	v_ashrrev_i32_e32 v7, 31, v6
	v_or_b32_e32 v4, s44, v4
	v_lshlrev_b64 v[6:7], 13, v[6:7]
	v_ashrrev_i32_e32 v5, 31, v4
	v_lshl_add_u64 v[6:7], s[96:97], 0, v[6:7]
	v_lshlrev_b64 v[4:5], 13, v[4:5]
	v_lshl_add_u64 v[6:7], v[6:7], 0, s[80:81]
	v_lshl_add_u64 v[4:5], v[2:3], 0, v[4:5]
	v_lshl_add_u64 v[6:7], v[6:7], 0, v[0:1]
	global_load_dwordx4 v[70:73], v[4:5], off
	global_load_dwordx4 v[66:69], v[6:7], off offset:2048
	v_or_b32_e32 v4, 28, v11
	v_bitop3_b32 v6, v10, 35, s19 bitop3:0x36
	v_cndmask_b32_e64 v4, v6, v4, s[40:41]
	v_or_b32_e32 v5, 28, v12
	v_bitop3_b32 v6, v10, 35, s52 bitop3:0x36
	v_or_b32_e32 v4, s44, v4
	v_cndmask_b32_e64 v6, v6, v5, s[40:41]
	v_ashrrev_i32_e32 v5, 31, v4
	v_lshlrev_b64 v[4:5], 13, v[4:5]
	v_lshl_add_u64 v[2:3], v[2:3], 0, v[4:5]
	v_or_b32_e32 v4, s44, v6
	v_ashrrev_i32_e32 v5, 31, v4
	v_lshlrev_b64 v[4:5], 13, v[4:5]
	v_lshl_add_u64 v[4:5], s[96:97], 0, v[4:5]
	v_lshl_add_u64 v[4:5], v[4:5], 0, s[80:81]
	v_and_b32_e32 v9, 63, v8
	v_lshl_add_u64 v[4:5], v[4:5], 0, v[0:1]
	v_bitop3_b32 v0, v8, 63, v8 bitop3:0xc
	v_cndmask_b32_e64 v0, v0, v9, s[40:41]
	global_load_dwordx4 v[78:81], v[2:3], off
	global_load_dwordx4 v[74:77], v[4:5], off offset:2048
	v_or_b32_e32 v2, s44, v0
	v_ashrrev_i32_e32 v3, 31, v2
	v_readlane_b32 s48, v251, 12
	v_lshlrev_b64 v[2:3], 8, v[2:3]
	v_readlane_b32 s49, v251, 13
	s_lshl_b32 s80, s58, 6
	s_lshl_b32 s44, s57, 2
	v_lshl_add_u64 v[2:3], s[48:49], 0, v[2:3]
	v_lshl_add_u64 v[2:3], v[2:3], 0, s[80:81]
	s_mov_b32 s45, s81
	v_lshl_add_u64 v[2:3], v[2:3], 0, s[44:45]
	global_load_dword v82, v[2:3], off
	s_add_u32 s45, s48, s80
	s_addc_u32 s48, s49, 0
	s_add_u32 s44, s45, s44
	s_addc_u32 s45, s48, 0
	s_lshl_b32 s60, s56, 8
	s_mov_b32 s61, 0
	s_mov_b32 s62, 0
	v_bfe_u32 v156, v188, 4, 2
	v_lshlrev_b32_e32 v157, 4, v188
	v_and_b32_e32 v157, 0xf0, v157
	v_mov_b32_e32 v158, v156
	v_or_b32_e32 v159, s19, v158
	v_xor_b32_e32 v160, 63, v159
	v_cndmask_b32_e64 v159, v160, v159, s[40:41]
	v_lshl_add_u32 v140, v159, 13, v157
	v_or_b32_e32 v159, s52, v158
	v_xor_b32_e32 v160, 63, v159
	v_cndmask_b32_e64 v159, v160, v159, s[40:41]
	v_lshl_add_u32 v141, v159, 13, v157
	v_or_b32_e32 v158, 4, v156
	v_or_b32_e32 v159, s19, v158
	v_xor_b32_e32 v160, 63, v159
	v_cndmask_b32_e64 v159, v160, v159, s[40:41]
	v_lshl_add_u32 v142, v159, 13, v157
	v_or_b32_e32 v159, s52, v158
	v_xor_b32_e32 v160, 63, v159
	v_cndmask_b32_e64 v159, v160, v159, s[40:41]
	v_lshl_add_u32 v143, v159, 13, v157
	v_or_b32_e32 v158, 8, v156
	v_or_b32_e32 v159, s19, v158
	v_xor_b32_e32 v160, 63, v159
	v_cndmask_b32_e64 v159, v160, v159, s[40:41]
	v_lshl_add_u32 v144, v159, 13, v157
	v_or_b32_e32 v159, s52, v158
	v_xor_b32_e32 v160, 63, v159
	v_cndmask_b32_e64 v159, v160, v159, s[40:41]
	v_lshl_add_u32 v145, v159, 13, v157
	v_or_b32_e32 v158, 12, v156
	v_or_b32_e32 v159, s19, v158
	v_xor_b32_e32 v160, 63, v159
	v_cndmask_b32_e64 v159, v160, v159, s[40:41]
	v_lshl_add_u32 v146, v159, 13, v157
	v_or_b32_e32 v159, s52, v158
	v_xor_b32_e32 v160, 63, v159
	v_cndmask_b32_e64 v159, v160, v159, s[40:41]
	v_lshl_add_u32 v147, v159, 13, v157
	v_or_b32_e32 v158, 16, v156
	v_or_b32_e32 v159, s19, v158
	v_xor_b32_e32 v160, 63, v159
	v_cndmask_b32_e64 v159, v160, v159, s[40:41]
	v_lshl_add_u32 v148, v159, 13, v157
	v_or_b32_e32 v159, s52, v158
	v_xor_b32_e32 v160, 63, v159
	v_cndmask_b32_e64 v159, v160, v159, s[40:41]
	v_lshl_add_u32 v149, v159, 13, v157
	v_or_b32_e32 v158, 20, v156
	v_or_b32_e32 v159, s19, v158
	v_xor_b32_e32 v160, 63, v159
	v_cndmask_b32_e64 v159, v160, v159, s[40:41]
	v_lshl_add_u32 v150, v159, 13, v157
	v_or_b32_e32 v159, s52, v158
	v_xor_b32_e32 v160, 63, v159
	v_cndmask_b32_e64 v159, v160, v159, s[40:41]
	v_lshl_add_u32 v151, v159, 13, v157
	v_or_b32_e32 v158, 24, v156
	v_or_b32_e32 v159, s19, v158
	v_xor_b32_e32 v160, 63, v159
	v_cndmask_b32_e64 v159, v160, v159, s[40:41]
	v_lshl_add_u32 v152, v159, 13, v157
	v_or_b32_e32 v159, s52, v158
	v_xor_b32_e32 v160, 63, v159
	v_cndmask_b32_e64 v159, v160, v159, s[40:41]
	v_lshl_add_u32 v153, v159, 13, v157
	v_or_b32_e32 v158, 28, v156
	v_or_b32_e32 v159, s19, v158
	v_xor_b32_e32 v160, 63, v159
	v_cndmask_b32_e64 v159, v160, v159, s[40:41]
	v_lshl_add_u32 v154, v159, 13, v157
	v_or_b32_e32 v159, s52, v158
	v_xor_b32_e32 v160, 63, v159
	v_cndmask_b32_e64 v159, v160, v159, s[40:41]
	v_lshl_add_u32 v155, v159, 13, v157
	s_branch .LBB0_383
